# norm0: next tile's x rows prefetched inside the narrow GEMM of the previous tile (first tile from the preheader)
# speedup vs baseline: 1.0026x; 1.0026x over previous
; DI int osgpr(int v) { asm volatile("" : "+s"(v)); return v; }
; DI void norm0_phase(const P& p, unsigned char* smem) {
;     ...
;     for (int rt = osgpr(blockIdx.x); rt < NROW / 16; rt += gridDim.x) {
;       for (int rr = 0; rr < 2; ++rr) {
;         const int row = rt * 16 + wave * 2 + rr;
;         const float* h = row < NLAT ? p.x + (size_t)row * DM : p.ctx + (size_t)(row - NLAT) * DM;
;         const int mr = row < NLAT ? (row >> 11) : 4;
;         f32x4 v[8]; float ss = 0.f;
; #pragma unroll
;         for (int i = 0; i < 8; ++i) { v[i] = __builtin_nontemporal_load((const f32x4*)(h + i * 256 + lane * 4)); ss += v[i][0] * v[i][0] + v[i][1] * v[i][1] + v[i][2] * v[i][2] + v[i][3] * v[i][3]; }
.LBB0_94:
	s_or_b64 exec, exec, s[6:7]
	s_waitcnt lgkmcnt(0)
	s_barrier
	s_load_dwordx2 s[92:93], s[0:1], 0x0
	s_load_dwordx2 s[90:91], s[0:1], 0x10
	s_load_dwordx2 s[6:7], s[0:1], 0x30
	v_readlane_b32 s28, v253, 0
	s_mov_b64 s[8:9], 0
	s_mov_b32 s10, 0
	s_mov_b32 s11, s28
	v_mov_b32_e32 v0, v166
	s_cmpk_gt_i32 s28, 0x23f
	v_mbcnt_lo_u32_b32 v167, -1, 0
	s_cbranch_scc1 .LBB0_115
	v_ashrrev_i32_e32 v1, 5, v0
	v_and_b32_e32 v69, -2, v1
	v_mbcnt_hi_u32_b32 v1, -1, v167
	v_and_b32_e32 v2, 64, v1
	v_add_u32_e32 v2, 64, v2
	v_xor_b32_e32 v3, 32, v1
	v_cmp_lt_i32_e32 vcc, v3, v2
	s_add_u32 s14, s68, s8
	s_addc_u32 s15, s69, s9
	v_cndmask_b32_e32 v3, v1, v3, vcc
	v_lshlrev_b32_e32 v72, 2, v3
	v_xor_b32_e32 v3, 16, v1
	v_cmp_lt_i32_e32 vcc, v3, v2
	s_add_i32 s29, s10, 0
	v_lshlrev_b32_e32 v0, 2, v0
	v_cndmask_b32_e32 v3, v1, v3, vcc
	v_lshlrev_b32_e32 v73, 2, v3
	v_xor_b32_e32 v3, 8, v1
	v_cmp_lt_i32_e32 vcc, v3, v2
	s_add_u32 s8, s14, 0x4800000
	v_and_b32_e32 v0, 0xfc, v0
	v_cndmask_b32_e32 v3, v1, v3, vcc
	v_lshlrev_b32_e32 v74, 2, v3
	v_xor_b32_e32 v3, 4, v1
	v_cmp_lt_i32_e32 vcc, v3, v2
	s_addc_u32 s9, s15, 0
	v_mov_b32_e32 v33, 0
	v_cndmask_b32_e32 v3, v1, v3, vcc
	v_lshlrev_b32_e32 v75, 2, v3
	v_xor_b32_e32 v3, 2, v1
	v_or_b32_e32 v8, 0x400, v0
	v_lshlrev_b32_e32 v32, 2, v0
	s_add_u32 s10, s14, 0x483c000
	v_cmp_lt_i32_e32 vcc, v3, v2
	v_or_b32_e32 v10, 0x500, v0
	s_waitcnt lgkmcnt(0)
	v_lshl_add_u64 v[34:35], s[6:7], 0, v[32:33]
	v_lshlrev_b32_e32 v32, 2, v8
	s_addc_u32 s11, s15, 0
	v_cndmask_b32_e32 v3, v1, v3, vcc
	v_or_b32_e32 v12, 0x600, v0
	v_lshl_add_u64 v[36:37], s[6:7], 0, v[32:33]
	v_lshlrev_b32_e32 v32, 2, v10
	v_lshlrev_b32_e32 v76, 2, v3
	v_xor_b32_e32 v3, 1, v1
	v_or_b32_e32 v14, 0x700, v0
	v_lshl_add_u64 v[38:39], s[6:7], 0, v[32:33]
	v_lshlrev_b32_e32 v32, 2, v12
	s_add_u32 s12, s14, 0x17e4d200
	v_cmp_lt_i32_e32 vcc, v3, v2
	v_lshl_add_u64 v[40:41], s[6:7], 0, v[32:33]
	v_lshlrev_b32_e32 v32, 2, v14
	s_addc_u32 s13, s15, 0
	v_cndmask_b32_e32 v1, v1, v3, vcc
	v_or_b32_e32 v2, 0x100, v0
	v_or_b32_e32 v4, 0x200, v0
	v_or_b32_e32 v6, 0x300, v0
	v_lshl_add_u64 v[42:43], s[6:7], 0, v[32:33]
	s_add_u32 s31, s14, 0x17ead200
	v_lshlrev_b32_e32 v32, 1, v0
	v_lshlrev_b32_e32 v77, 2, v1
	s_movk_i32 s30, 0x300
	s_addc_u32 s34, s15, 0
	v_lshl_add_u64 v[44:45], s[10:11], 0, v[32:33]
	s_lshl_b32 s35, s28, 4
	s_lshl_b32 s36, s70, 4
	s_movk_i32 s37, 0x1fff
	v_lshlrev_b32_e32 v32, 2, v0
	s_movk_i32 s38, 0x1000
	v_mov_b32_e32 v78, 0x358637bd
	s_mov_b32 s39, 0x800000
	s_mov_b64 s[14:15], 0x2000
	v_lshlrev_b32_e32 v46, 2, v2
	v_lshlrev_b32_e32 v48, 2, v4
	v_lshlrev_b32_e32 v50, 2, v6
	v_lshlrev_b32_e32 v52, 2, v8
	v_lshlrev_b32_e32 v54, 2, v10
	v_lshlrev_b32_e32 v56, 2, v12
	v_lshlrev_b32_e32 v58, 2, v14
	s_mov_b32 s40, 0x10000
	s_mov_b32 s41, 0x20000
	s_movk_i32 s42, 0x1ff
	s_mov_b64 s[16:17], 0x800
	s_movk_i32 s43, 0xff
	v_readfirstlane_b32 s46, v69
	v_and_b32_e32 v94, 63, v166
	s_lshl_b32 s45, s28, 4
	v_lshlrev_b32_e32 v94, 4, v94
	s_add_u32 s45, s45, s46
	v_add_u32_e32 v95, 0x1000, v94
	s_sub_u32 s46, s45, 0x2000
	s_cmpk_ge_u32 s45, 0x2000
	s_cselect_b32 s98, s90, s92
	s_cselect_b32 s99, s91, s93
	s_cselect_b32 s46, s46, s45
	s_lshl_b32 s46, s46, 13
	s_add_u32 s98, s98, s46
	s_addc_u32 s99, s99, 0
	s_add_u32 s100, s98, 0x2000
	s_addc_u32 s101, s99, 0
	global_load_dwordx4 v[112:115], v94, s[98:99] offset:0 nt
	global_load_dwordx4 v[116:119], v94, s[98:99] offset:1024 nt
	global_load_dwordx4 v[120:123], v94, s[98:99] offset:2048 nt
	global_load_dwordx4 v[124:127], v94, s[98:99] offset:3072 nt
	global_load_dwordx4 v[128:131], v95, s[98:99] offset:0 nt
	global_load_dwordx4 v[132:135], v95, s[98:99] offset:1024 nt
	global_load_dwordx4 v[136:139], v95, s[98:99] offset:2048 nt
	global_load_dwordx4 v[140:143], v95, s[98:99] offset:3072 nt
	global_load_dwordx4 v[144:147], v94, s[100:101] offset:0 nt
	global_load_dwordx4 v[148:151], v94, s[100:101] offset:1024 nt
	global_load_dwordx4 v[152:155], v94, s[100:101] offset:2048 nt
	global_load_dwordx4 v[156:159], v94, s[100:101] offset:3072 nt
	global_load_dwordx4 v[160:163], v95, s[100:101] offset:0 nt
	global_load_dwordx4 v[232:235], v95, s[100:101] offset:1024 nt
	global_load_dwordx4 v[236:239], v95, s[100:101] offset:2048 nt
	global_load_dwordx4 v[240:243], v95, s[100:101] offset:3072 nt
	s_branch .LBB0_97

; DI void norm0_phase(const P& p, unsigned char* smem) {
;     ...
;         const int row = rt * 16 + wave * 2 + rr;
;         const float* h = row < NLAT ? p.x + (size_t)row * DM : p.ctx + (size_t)(row - NLAT) * DM;
;         const int mr = row < NLAT ? (row >> 11) : 4;
;         f32x4 v[8]; float ss = 0.f;
; #pragma unroll
;         for (int i = 0; i < 8; ++i) { v[i] = __builtin_nontemporal_load((const f32x4*)(h + i * 256 + lane * 4)); ss += v[i][0] * v[i][0] + v[i][1] * v[i][1] + v[i][2] * v[i][2] + v[i][3] * v[i][3]; }
;         ss = wave_sum(ss);
;         const float rstd = rsqrtf(ss * (1.f / 2048.f) + 1e-6f);
;         const float* md = mod + (size_t)mr * 6144;
; #pragma unroll
;         for (int i = 0; i < 8; ++i) {
;             const int j = i * 256 + lane * 4;
;             const f32x4 gw = *(const f32x4*)(p.norm_pre + j), sh = *(const f32x4*)(md + j), scl = *(const f32x4*)(md + 2048 + j);
.LBB0_97:
	s_lshl_b32 s24, s28, 4
	v_add_u32_e32 v79, s24, v69
	v_ashrrev_i32_e32 v0, 11, v79
	v_mul_hi_i32_i24_e32 v61, 0x6000, v0
	v_mul_i32_i24_e32 v60, 0x6000, v0
	s_mov_b64 s[18:19], -1
	v_and_b32_e32 v4, 63, v166
	v_readfirstlane_b32 s20, v69
	v_lshlrev_b32_e32 v0, 4, v4
	v_lshlrev_b32_e32 v2, 3, v4
	v_add_u32_e32 v1, 0x1000, v0
	v_add_u32_e32 v3, 0x1000, v2
	s_add_u32 s20, s24, s20
	s_lshr_b32 s25, s20, 11
	s_cmpk_ge_u32 s20, 0x2000
	s_cselect_b32 s25, 4, s25
	s_mul_i32 s25, s25, 0x6000
	s_add_u32 s22, s8, s25
	s_addc_u32 s23, s9, 0
	s_add_u32 s48, s22, 0x2000
	s_addc_u32 s49, s23, 0
	s_lshl_b32 s25, s20, 12
	s_add_u32 s26, s10, s25
	s_addc_u32 s27, s11, 0
	global_load_dwordx4 v[80:83], v0, s[6:7] offset:0
	global_load_dwordx4 v[84:87], v0, s[6:7] offset:1024
	global_load_dwordx4 v[88:91], v0, s[6:7] offset:2048
	global_load_dwordx4 v[92:95], v0, s[6:7] offset:3072
	global_load_dwordx4 v[96:99], v1, s[6:7] offset:0
	global_load_dwordx4 v[100:103], v1, s[6:7] offset:1024
	global_load_dwordx4 v[104:107], v1, s[6:7] offset:2048
	global_load_dwordx4 v[108:111], v1, s[6:7] offset:3072
	global_load_dwordx4 v[168:171], v0, s[22:23] offset:0
	global_load_dwordx4 v[200:203], v0, s[48:49] offset:0
	global_load_dwordx4 v[172:175], v0, s[22:23] offset:1024
	global_load_dwordx4 v[204:207], v0, s[48:49] offset:1024
	global_load_dwordx4 v[176:179], v0, s[22:23] offset:2048
	global_load_dwordx4 v[208:211], v0, s[48:49] offset:2048
	global_load_dwordx4 v[180:183], v0, s[22:23] offset:3072
	global_load_dwordx4 v[212:215], v0, s[48:49] offset:3072
	global_load_dwordx4 v[184:187], v1, s[22:23] offset:0
	global_load_dwordx4 v[216:219], v1, s[48:49] offset:0
	global_load_dwordx4 v[188:191], v1, s[22:23] offset:1024
	global_load_dwordx4 v[220:223], v1, s[48:49] offset:1024
	global_load_dwordx4 v[192:195], v1, s[22:23] offset:2048
	global_load_dwordx4 v[224:227], v1, s[48:49] offset:2048
	global_load_dwordx4 v[196:199], v1, s[22:23] offset:3072
	global_load_dwordx4 v[228:231], v1, s[48:49] offset:3072
	s_waitcnt vmcnt(24)
	v_mul_f32_e32 v4, v112, v112
	v_mul_f32_e32 v5, v113, v113
	v_fmac_f32_e32 v4, v114, v114
	v_fmac_f32_e32 v5, v115, v115
	v_fmac_f32_e32 v4, v116, v116
	v_fmac_f32_e32 v5, v117, v117
	v_fmac_f32_e32 v4, v118, v118
	v_fmac_f32_e32 v5, v119, v119
	v_fmac_f32_e32 v4, v120, v120
	v_fmac_f32_e32 v5, v121, v121
	v_fmac_f32_e32 v4, v122, v122
	v_fmac_f32_e32 v5, v123, v123
	v_fmac_f32_e32 v4, v124, v124
	v_fmac_f32_e32 v5, v125, v125
	v_fmac_f32_e32 v4, v126, v126
	v_fmac_f32_e32 v5, v127, v127
	v_fmac_f32_e32 v4, v128, v128
	v_fmac_f32_e32 v5, v129, v129
	v_fmac_f32_e32 v4, v130, v130
	v_fmac_f32_e32 v5, v131, v131
	v_fmac_f32_e32 v4, v132, v132
	v_fmac_f32_e32 v5, v133, v133
	v_fmac_f32_e32 v4, v134, v134
	v_fmac_f32_e32 v5, v135, v135
	v_fmac_f32_e32 v4, v136, v136
	v_fmac_f32_e32 v5, v137, v137
	v_fmac_f32_e32 v4, v138, v138
	v_fmac_f32_e32 v5, v139, v139
	v_fmac_f32_e32 v4, v140, v140
	v_fmac_f32_e32 v5, v141, v141
	v_fmac_f32_e32 v4, v142, v142
	v_fmac_f32_e32 v5, v143, v143
	v_add_f32_e32 v4, v4, v5
	v_mul_f32_e32 v6, v144, v144
	v_mul_f32_e32 v7, v145, v145
	v_fmac_f32_e32 v6, v146, v146
	v_fmac_f32_e32 v7, v147, v147
	v_fmac_f32_e32 v6, v148, v148
	v_fmac_f32_e32 v7, v149, v149
	v_fmac_f32_e32 v6, v150, v150
	v_fmac_f32_e32 v7, v151, v151
	v_fmac_f32_e32 v6, v152, v152
	v_fmac_f32_e32 v7, v153, v153
	v_fmac_f32_e32 v6, v154, v154
	v_fmac_f32_e32 v7, v155, v155
	v_fmac_f32_e32 v6, v156, v156
	v_fmac_f32_e32 v7, v157, v157
	v_fmac_f32_e32 v6, v158, v158
	v_fmac_f32_e32 v7, v159, v159
	v_fmac_f32_e32 v6, v160, v160
	v_fmac_f32_e32 v7, v161, v161
	v_fmac_f32_e32 v6, v162, v162
	v_fmac_f32_e32 v7, v163, v163
	v_fmac_f32_e32 v6, v232, v232
	v_fmac_f32_e32 v7, v233, v233
	v_fmac_f32_e32 v6, v234, v234
	v_fmac_f32_e32 v7, v235, v235
	v_fmac_f32_e32 v6, v236, v236
	v_fmac_f32_e32 v7, v237, v237
	v_fmac_f32_e32 v6, v238, v238
	v_fmac_f32_e32 v7, v239, v239
	v_fmac_f32_e32 v6, v240, v240
	v_fmac_f32_e32 v7, v241, v241
	v_fmac_f32_e32 v6, v242, v242
	v_fmac_f32_e32 v7, v243, v243
	v_add_f32_e32 v6, v6, v7
	ds_bpermute_b32 v8, v72, v4
	ds_bpermute_b32 v9, v72, v6
	s_waitcnt lgkmcnt(1)
	v_add_f32_e32 v4, v4, v8
	s_waitcnt lgkmcnt(0)
	v_add_f32_e32 v6, v6, v9
	ds_bpermute_b32 v8, v73, v4
	ds_bpermute_b32 v9, v73, v6
	s_waitcnt lgkmcnt(1)
	v_add_f32_e32 v4, v4, v8
	s_waitcnt lgkmcnt(0)
	v_add_f32_e32 v6, v6, v9
	ds_bpermute_b32 v8, v74, v4
	ds_bpermute_b32 v9, v74, v6
	s_waitcnt lgkmcnt(1)
	v_add_f32_e32 v4, v4, v8
	s_waitcnt lgkmcnt(0)
	v_add_f32_e32 v6, v6, v9
	ds_bpermute_b32 v8, v75, v4
	ds_bpermute_b32 v9, v75, v6
	s_waitcnt lgkmcnt(1)
	v_add_f32_e32 v4, v4, v8
	s_waitcnt lgkmcnt(0)
	v_add_f32_e32 v6, v6, v9
	ds_bpermute_b32 v8, v76, v4
	ds_bpermute_b32 v9, v76, v6
	s_waitcnt lgkmcnt(1)
	v_add_f32_e32 v4, v4, v8
	s_waitcnt lgkmcnt(0)
	v_add_f32_e32 v6, v6, v9
	ds_bpermute_b32 v8, v77, v4
	ds_bpermute_b32 v9, v77, v6
	s_waitcnt lgkmcnt(1)
	v_add_f32_e32 v4, v4, v8
	s_waitcnt lgkmcnt(0)
	v_add_f32_e32 v6, v6, v9
	v_fmamk_f32 v4, v4, 0x3a000000, v78
	v_fmamk_f32 v6, v6, 0x3a000000, v78
	v_rsq_f32_e32 v10, v4
	v_rsq_f32_e32 v11, v6
	s_waitcnt vmcnt(16)
	v_mul_f32_e32 v12, v112, v10
	v_mul_f32_e32 v13, v113, v10
	v_mul_f32_e32 v14, v114, v10
	v_mul_f32_e32 v15, v115, v10
	v_mul_f32_e32 v12, v12, v80
	v_mul_f32_e32 v13, v13, v81
	v_mul_f32_e32 v14, v14, v82
	v_mul_f32_e32 v15, v15, v83
	s_waitcnt vmcnt(14)
; DI void norm0_phase(const P& p, unsigned char* smem) {
;     ...
;         for (int i = 0; i < 8; ++i) {
;             const int j = i * 256 + lane * 4;
;             const f32x4 gw = *(const f32x4*)(p.norm_pre + j), sh = *(const f32x4*)(md + j), scl = *(const f32x4*)(md + 2048 + j);
;             float o[4];
; #pragma unroll
;             for (int e = 0; e < 4; ++e) o[e] = v[i][e] * rstd * gw[e] * (1.f + scl[e]) + sh[e];
;             u32x2 w; w.x = pk2(o[0], o[1]); w.y = pk2(o[2], o[3]);
;             *(u32x2*)(nb + (size_t)row * DM + j) = w;
	v_add_f32_e32 v16, 1.0, v200
	v_add_f32_e32 v17, 1.0, v201
	v_add_f32_e32 v18, 1.0, v202
	v_add_f32_e32 v19, 1.0, v203
	v_fma_f32 v12, v12, v16, v168
	v_fma_f32 v13, v13, v17, v169
	v_fma_f32 v14, v14, v18, v170
	v_fma_f32 v15, v15, v19, v171
	v_cvt_pk_bf16_f32 v20, v12, v13
	v_cvt_pk_bf16_f32 v21, v14, v15
	global_store_dwordx2 v2, v[20:21], s[26:27] offset:0
	v_mul_f32_e32 v12, v116, v10
	v_mul_f32_e32 v13, v117, v10
	v_mul_f32_e32 v14, v118, v10
	v_mul_f32_e32 v15, v119, v10
	v_mul_f32_e32 v12, v12, v84
	v_mul_f32_e32 v13, v13, v85
	v_mul_f32_e32 v14, v14, v86
	v_mul_f32_e32 v15, v15, v87
	s_waitcnt vmcnt(12)
	v_add_f32_e32 v16, 1.0, v204
	v_add_f32_e32 v17, 1.0, v205
	v_add_f32_e32 v18, 1.0, v206
	v_add_f32_e32 v19, 1.0, v207
	v_fma_f32 v12, v12, v16, v172
	v_fma_f32 v13, v13, v17, v173
	v_fma_f32 v14, v14, v18, v174
	v_fma_f32 v15, v15, v19, v175
	v_cvt_pk_bf16_f32 v22, v12, v13
	v_cvt_pk_bf16_f32 v23, v14, v15
	global_store_dwordx2 v2, v[22:23], s[26:27] offset:512
	v_mul_f32_e32 v12, v120, v10
	v_mul_f32_e32 v13, v121, v10
	v_mul_f32_e32 v14, v122, v10
	v_mul_f32_e32 v15, v123, v10
	v_mul_f32_e32 v12, v12, v88
	v_mul_f32_e32 v13, v13, v89
	v_mul_f32_e32 v14, v14, v90
	v_mul_f32_e32 v15, v15, v91
	s_waitcnt vmcnt(10)
	v_add_f32_e32 v16, 1.0, v208
	v_add_f32_e32 v17, 1.0, v209
	v_add_f32_e32 v18, 1.0, v210
	v_add_f32_e32 v19, 1.0, v211
	v_fma_f32 v12, v12, v16, v176
	v_fma_f32 v13, v13, v17, v177
	v_fma_f32 v14, v14, v18, v178
	v_fma_f32 v15, v15, v19, v179
	v_cvt_pk_bf16_f32 v20, v12, v13
	v_cvt_pk_bf16_f32 v21, v14, v15
	global_store_dwordx2 v2, v[20:21], s[26:27] offset:1024
	v_mul_f32_e32 v12, v124, v10
	v_mul_f32_e32 v13, v125, v10
	v_mul_f32_e32 v14, v126, v10
	v_mul_f32_e32 v15, v127, v10
	v_mul_f32_e32 v12, v12, v92
	v_mul_f32_e32 v13, v13, v93
	v_mul_f32_e32 v14, v14, v94
	v_mul_f32_e32 v15, v15, v95
	s_waitcnt vmcnt(8)
	v_add_f32_e32 v16, 1.0, v212
	v_add_f32_e32 v17, 1.0, v213
	v_add_f32_e32 v18, 1.0, v214
	v_add_f32_e32 v19, 1.0, v215
	v_fma_f32 v12, v12, v16, v180
	v_fma_f32 v13, v13, v17, v181
	v_fma_f32 v14, v14, v18, v182
	v_fma_f32 v15, v15, v19, v183
	v_cvt_pk_bf16_f32 v22, v12, v13
	v_cvt_pk_bf16_f32 v23, v14, v15
	global_store_dwordx2 v2, v[22:23], s[26:27] offset:1536
	v_mul_f32_e32 v12, v128, v10
	v_mul_f32_e32 v13, v129, v10
	v_mul_f32_e32 v14, v130, v10
	v_mul_f32_e32 v15, v131, v10
	v_mul_f32_e32 v12, v12, v96
	v_mul_f32_e32 v13, v13, v97
	v_mul_f32_e32 v14, v14, v98
	v_mul_f32_e32 v15, v15, v99
	s_waitcnt vmcnt(6)
	v_add_f32_e32 v16, 1.0, v216
	v_add_f32_e32 v17, 1.0, v217
	v_add_f32_e32 v18, 1.0, v218
	v_add_f32_e32 v19, 1.0, v219
	v_fma_f32 v12, v12, v16, v184
	v_fma_f32 v13, v13, v17, v185
	v_fma_f32 v14, v14, v18, v186
	v_fma_f32 v15, v15, v19, v187
	v_cvt_pk_bf16_f32 v20, v12, v13
	v_cvt_pk_bf16_f32 v21, v14, v15
	global_store_dwordx2 v2, v[20:21], s[26:27] offset:2048
	v_mul_f32_e32 v12, v132, v10
	v_mul_f32_e32 v13, v133, v10
	v_mul_f32_e32 v14, v134, v10
	v_mul_f32_e32 v15, v135, v10
	v_mul_f32_e32 v12, v12, v100
	v_mul_f32_e32 v13, v13, v101
	v_mul_f32_e32 v14, v14, v102
	v_mul_f32_e32 v15, v15, v103
	s_waitcnt vmcnt(4)
	v_add_f32_e32 v16, 1.0, v220
	v_add_f32_e32 v17, 1.0, v221
	v_add_f32_e32 v18, 1.0, v222
	v_add_f32_e32 v19, 1.0, v223
	v_fma_f32 v12, v12, v16, v188
	v_fma_f32 v13, v13, v17, v189
	v_fma_f32 v14, v14, v18, v190
	v_fma_f32 v15, v15, v19, v191
	v_cvt_pk_bf16_f32 v22, v12, v13
	v_cvt_pk_bf16_f32 v23, v14, v15
	global_store_dwordx2 v2, v[22:23], s[26:27] offset:2560
	v_mul_f32_e32 v12, v136, v10
	v_mul_f32_e32 v13, v137, v10
	v_mul_f32_e32 v14, v138, v10
	v_mul_f32_e32 v15, v139, v10
	v_mul_f32_e32 v12, v12, v104
	v_mul_f32_e32 v13, v13, v105
	v_mul_f32_e32 v14, v14, v106
	v_mul_f32_e32 v15, v15, v107
	s_waitcnt vmcnt(2)
	v_add_f32_e32 v16, 1.0, v224
	v_add_f32_e32 v17, 1.0, v225
	v_add_f32_e32 v18, 1.0, v226
	v_add_f32_e32 v19, 1.0, v227
	v_fma_f32 v12, v12, v16, v192
	v_fma_f32 v13, v13, v17, v193
	v_fma_f32 v14, v14, v18, v194
	v_fma_f32 v15, v15, v19, v195
	v_cvt_pk_bf16_f32 v20, v12, v13
	v_cvt_pk_bf16_f32 v21, v14, v15
	global_store_dwordx2 v2, v[20:21], s[26:27] offset:3072
	v_mul_f32_e32 v12, v140, v10
	v_mul_f32_e32 v13, v141, v10
	v_mul_f32_e32 v14, v142, v10
	v_mul_f32_e32 v15, v143, v10
	v_mul_f32_e32 v12, v12, v108
	v_mul_f32_e32 v13, v13, v109
	v_mul_f32_e32 v14, v14, v110
	v_mul_f32_e32 v15, v15, v111
	s_waitcnt vmcnt(0)
; DI void norm0_phase(const P& p, unsigned char* smem) {
;     ...
;         for (int i = 0; i < 8; ++i) {
;             const int j = i * 256 + lane * 4;
;             const f32x4 gw = *(const f32x4*)(p.norm_pre + j), sh = *(const f32x4*)(md + j), scl = *(const f32x4*)(md + 2048 + j);
;             float o[4];
; #pragma unroll
;             for (int e = 0; e < 4; ++e) o[e] = v[i][e] * rstd * gw[e] * (1.f + scl[e]) + sh[e];
;             u32x2 w; w.x = pk2(o[0], o[1]); w.y = pk2(o[2], o[3]);
;             *(u32x2*)(nb + (size_t)row * DM + j) = w;
	v_add_f32_e32 v16, 1.0, v228
	v_add_f32_e32 v17, 1.0, v229
	v_add_f32_e32 v18, 1.0, v230
	v_add_f32_e32 v19, 1.0, v231
	v_fma_f32 v12, v12, v16, v196
	v_fma_f32 v13, v13, v17, v197
	v_fma_f32 v14, v14, v18, v198
	v_fma_f32 v15, v15, v19, v199
	v_cvt_pk_bf16_f32 v22, v12, v13
	v_cvt_pk_bf16_f32 v23, v14, v15
	global_store_dwordx2 v2, v[22:23], s[26:27] offset:3584
	v_mul_f32_e32 v12, v144, v11
	v_mul_f32_e32 v13, v145, v11
	v_mul_f32_e32 v14, v146, v11
	v_mul_f32_e32 v15, v147, v11
	v_mul_f32_e32 v12, v12, v80
	v_mul_f32_e32 v13, v13, v81
	v_mul_f32_e32 v14, v14, v82
	v_mul_f32_e32 v15, v15, v83
	v_add_f32_e32 v16, 1.0, v200
	v_add_f32_e32 v17, 1.0, v201
	v_add_f32_e32 v18, 1.0, v202
	v_add_f32_e32 v19, 1.0, v203
	v_fma_f32 v12, v12, v16, v168
	v_fma_f32 v13, v13, v17, v169
	v_fma_f32 v14, v14, v18, v170
	v_fma_f32 v15, v15, v19, v171
	v_cvt_pk_bf16_f32 v20, v12, v13
	v_cvt_pk_bf16_f32 v21, v14, v15
	global_store_dwordx2 v3, v[20:21], s[26:27] offset:0
	v_mul_f32_e32 v12, v148, v11
	v_mul_f32_e32 v13, v149, v11
	v_mul_f32_e32 v14, v150, v11
	v_mul_f32_e32 v15, v151, v11
	v_mul_f32_e32 v12, v12, v84
	v_mul_f32_e32 v13, v13, v85
	v_mul_f32_e32 v14, v14, v86
	v_mul_f32_e32 v15, v15, v87
	v_add_f32_e32 v16, 1.0, v204
	v_add_f32_e32 v17, 1.0, v205
	v_add_f32_e32 v18, 1.0, v206
	v_add_f32_e32 v19, 1.0, v207
	v_fma_f32 v12, v12, v16, v172
	v_fma_f32 v13, v13, v17, v173
	v_fma_f32 v14, v14, v18, v174
	v_fma_f32 v15, v15, v19, v175
	v_cvt_pk_bf16_f32 v22, v12, v13
	v_cvt_pk_bf16_f32 v23, v14, v15
	global_store_dwordx2 v3, v[22:23], s[26:27] offset:512
	v_mul_f32_e32 v12, v152, v11
	v_mul_f32_e32 v13, v153, v11
	v_mul_f32_e32 v14, v154, v11
	v_mul_f32_e32 v15, v155, v11
	v_mul_f32_e32 v12, v12, v88
	v_mul_f32_e32 v13, v13, v89
	v_mul_f32_e32 v14, v14, v90
	v_mul_f32_e32 v15, v15, v91
	v_add_f32_e32 v16, 1.0, v208
	v_add_f32_e32 v17, 1.0, v209
	v_add_f32_e32 v18, 1.0, v210
	v_add_f32_e32 v19, 1.0, v211
	v_fma_f32 v12, v12, v16, v176
	v_fma_f32 v13, v13, v17, v177
	v_fma_f32 v14, v14, v18, v178
	v_fma_f32 v15, v15, v19, v179
	v_cvt_pk_bf16_f32 v20, v12, v13
	v_cvt_pk_bf16_f32 v21, v14, v15
	global_store_dwordx2 v3, v[20:21], s[26:27] offset:1024
	v_mul_f32_e32 v12, v156, v11
	v_mul_f32_e32 v13, v157, v11
	v_mul_f32_e32 v14, v158, v11
	v_mul_f32_e32 v15, v159, v11
	v_mul_f32_e32 v12, v12, v92
	v_mul_f32_e32 v13, v13, v93
	v_mul_f32_e32 v14, v14, v94
	v_mul_f32_e32 v15, v15, v95
	v_add_f32_e32 v16, 1.0, v212
	v_add_f32_e32 v17, 1.0, v213
	v_add_f32_e32 v18, 1.0, v214
	v_add_f32_e32 v19, 1.0, v215
	v_fma_f32 v12, v12, v16, v180
	v_fma_f32 v13, v13, v17, v181
	v_fma_f32 v14, v14, v18, v182
	v_fma_f32 v15, v15, v19, v183
	v_cvt_pk_bf16_f32 v22, v12, v13
	v_cvt_pk_bf16_f32 v23, v14, v15
	global_store_dwordx2 v3, v[22:23], s[26:27] offset:1536
	v_mul_f32_e32 v12, v160, v11
	v_mul_f32_e32 v13, v161, v11
	v_mul_f32_e32 v14, v162, v11
	v_mul_f32_e32 v15, v163, v11
	v_mul_f32_e32 v12, v12, v96
	v_mul_f32_e32 v13, v13, v97
	v_mul_f32_e32 v14, v14, v98
	v_mul_f32_e32 v15, v15, v99
	v_add_f32_e32 v16, 1.0, v216
	v_add_f32_e32 v17, 1.0, v217
	v_add_f32_e32 v18, 1.0, v218
	v_add_f32_e32 v19, 1.0, v219
	v_fma_f32 v12, v12, v16, v184
	v_fma_f32 v13, v13, v17, v185
	v_fma_f32 v14, v14, v18, v186
	v_fma_f32 v15, v15, v19, v187
	v_cvt_pk_bf16_f32 v20, v12, v13
	v_cvt_pk_bf16_f32 v21, v14, v15
	global_store_dwordx2 v3, v[20:21], s[26:27] offset:2048
	v_mul_f32_e32 v12, v232, v11
	v_mul_f32_e32 v13, v233, v11
	v_mul_f32_e32 v14, v234, v11
	v_mul_f32_e32 v15, v235, v11
	v_mul_f32_e32 v12, v12, v100
	v_mul_f32_e32 v13, v13, v101
	v_mul_f32_e32 v14, v14, v102
	v_mul_f32_e32 v15, v15, v103
	v_add_f32_e32 v16, 1.0, v220
	v_add_f32_e32 v17, 1.0, v221
	v_add_f32_e32 v18, 1.0, v222
	v_add_f32_e32 v19, 1.0, v223
	v_fma_f32 v12, v12, v16, v188
	v_fma_f32 v13, v13, v17, v189
	v_fma_f32 v14, v14, v18, v190
	v_fma_f32 v15, v15, v19, v191
	v_cvt_pk_bf16_f32 v22, v12, v13
	v_cvt_pk_bf16_f32 v23, v14, v15
	global_store_dwordx2 v3, v[22:23], s[26:27] offset:2560
	v_mul_f32_e32 v12, v236, v11
	v_mul_f32_e32 v13, v237, v11
	v_mul_f32_e32 v14, v238, v11
	v_mul_f32_e32 v15, v239, v11
	v_mul_f32_e32 v12, v12, v104
	v_mul_f32_e32 v13, v13, v105
	v_mul_f32_e32 v14, v14, v106
	v_mul_f32_e32 v15, v15, v107
	v_add_f32_e32 v16, 1.0, v224
	v_add_f32_e32 v17, 1.0, v225
	v_add_f32_e32 v18, 1.0, v226
	v_add_f32_e32 v19, 1.0, v227
	v_fma_f32 v12, v12, v16, v192
	v_fma_f32 v13, v13, v17, v193
	v_fma_f32 v14, v14, v18, v194
	v_fma_f32 v15, v15, v19, v195
	v_cvt_pk_bf16_f32 v20, v12, v13
	v_cvt_pk_bf16_f32 v21, v14, v15
	global_store_dwordx2 v3, v[20:21], s[26:27] offset:3072
	v_mul_f32_e32 v12, v240, v11
	v_mul_f32_e32 v13, v241, v11
	v_mul_f32_e32 v14, v242, v11
	v_mul_f32_e32 v15, v243, v11
	v_mul_f32_e32 v12, v12, v108
	v_mul_f32_e32 v13, v13, v109
	v_mul_f32_e32 v14, v14, v110
	v_mul_f32_e32 v15, v15, v111
	v_add_f32_e32 v16, 1.0, v228
	v_add_f32_e32 v17, 1.0, v229
	v_add_f32_e32 v18, 1.0, v230
	v_add_f32_e32 v19, 1.0, v231
	v_fma_f32 v12, v12, v16, v196
	v_fma_f32 v13, v13, v17, v197
	v_fma_f32 v14, v14, v18, v198
	v_fma_f32 v15, v15, v19, v199
	v_cvt_pk_bf16_f32 v22, v12, v13
	v_cvt_pk_bf16_f32 v23, v14, v15
	global_store_dwordx2 v3, v[22:23], s[26:27] offset:3584
; DI f32x4 mfma16(bf16x8 a, bf16x8 b, f32x4 c) { return __builtin_amdgcn_mfma_f32_16x16x32_bf16(a, b, c, 0, 0, 0); }
; DI int otid() { int t = threadIdx.x; asm volatile("" : "+v"(t)); return t; }
; DI int osgpr(int v) { asm volatile("" : "+s"(v)); return v; }
; DI void skinny_tile(const P& p, int l, int r0, float* red) {
;     const bf16_t* A = (const bf16_t*)(p.ws + WS_NBUF);
;     const bf16_t* Bt = (const bf16_t*)(p.ws + WS_WNT) + (size_t)l * NNAR * DM;
;     float* G = (float*)(p.ws + WS_G);
;     const int tid = otid(), w = tid >> 6, lane = tid & 63, l15 = lane & 15, g = lane >> 4;
;     f32x4 acc[3];
; #pragma unroll
;     for (int n = 0; n < 3; ++n) acc[n] = (f32x4){0.f, 0.f, 0.f, 0.f};
;     const bf16_t* ap = A + (size_t)(r0 + l15) * DM + 256 * w + 8 * g;
;     const bf16_t* bp = Bt + (size_t)l15 * DM + 256 * w + 8 * g;
; #pragma unroll
;     for (int ks = 0; ks < 8; ++ks) {
;         const bf16x8 a0 = *(const bf16x8*)(ap + 32 * ks);
; #pragma unroll
;         for (int n = 0; n < 3; ++n) acc[n] = mfma16(a0, *(const bf16x8*)(bp + (size_t)16 * n * DM + 32 * ks), acc[n]);
;     }
; DI void norm0_phase(const P& p, unsigned char* smem) {
;     ...
;     for (int rt = osgpr(blockIdx.x); rt < NROW / 16; rt += gridDim.x) {
;       for (int rr = 0; rr < 2; ++rr) {
;         const int row = rt * 16 + wave * 2 + rr;
;         const float* h = row < NLAT ? p.x + (size_t)row * DM : p.ctx + (size_t)(row - NLAT) * DM;
;         const int mr = row < NLAT ? (row >> 11) : 4;
;         f32x4 v[8]; float ss = 0.f;
; #pragma unroll
;         for (int i = 0; i < 8; ++i) { v[i] = __builtin_nontemporal_load((const f32x4*)(h + i * 256 + lane * 4)); ss += v[i][0] * v[i][0] + v[i][1] * v[i][1] + v[i][2] * v[i][2] + v[i][3] * v[i][3]; }
.LBB0_103:
	v_mov_b32_e32 v0, v166
	s_waitcnt vmcnt(0)
	s_barrier
	v_mov_b32_e32 v9, v33
	v_and_b32_e32 v47, 15, v0
	v_ashrrev_i32_e32 v1, 6, v0
	v_or_b32_e32 v2, s24, v47
	v_ashrrev_i32_e32 v3, 31, v2
	v_lshlrev_b32_e32 v4, 8, v1
	v_lshlrev_b64 v[2:3], 12, v[2:3]
	v_ashrrev_i32_e32 v5, 31, v4
	v_bfe_u32 v49, v0, 4, 2
	v_lshl_add_u64 v[2:3], s[10:11], 0, v[2:3]
	v_lshlrev_b64 v[6:7], 1, v[4:5]
	v_lshl_add_u64 v[2:3], v[2:3], 0, v[6:7]
	v_lshlrev_b32_e32 v8, 4, v49
	v_lshl_add_u64 v[30:31], v[2:3], 0, v[8:9]
	v_lshlrev_b32_e32 v2, 12, v47
	v_mov_b32_e32 v3, v33
	v_lshl_add_u64 v[10:11], s[12:13], 0, v[2:3]
	global_load_dwordx4 v[2:5], v[30:31], off
	v_lshl_add_u64 v[6:7], v[10:11], 0, v[6:7]
	v_lshl_add_u64 v[70:71], v[6:7], 0, v[8:9]
	global_load_dwordx4 v[6:9], v[70:71], off
	v_add_co_u32_e32 v88, vcc, s40, v70
	v_mul_lo_u32 v1, v1, s30
	s_nop 0
	v_addc_co_u32_e32 v89, vcc, 0, v71, vcc
	global_load_dwordx4 v[10:13], v[88:89], off
	v_add_co_u32_e32 v90, vcc, s41, v70
	v_or_b32_e32 v1, v1, v47
	s_nop 0
	v_addc_co_u32_e32 v91, vcc, 0, v71, vcc
	global_load_dwordx4 v[14:17], v[90:91], off
	global_load_dwordx4 v[18:21], v[30:31], off offset:64
	global_load_dwordx4 v[22:25], v[70:71], off offset:64
	global_load_dwordx4 v[26:29], v[88:89], off offset:64
	global_load_dwordx4 v[60:63], v[90:91], off offset:64
	global_load_dwordx4 v[64:67], v[30:31], off offset:128
	global_load_dwordx4 v[80:83], v[70:71], off offset:128
	v_lshlrev_b32_e32 v1, 2, v1
	v_cmp_gt_i32_e32 vcc, s30, v0
	s_waitcnt vmcnt(8)
	v_mfma_f32_16x16x32_bf16 v[6:9], v[2:5], v[6:9], 0
	s_waitcnt vmcnt(7)
	v_mfma_f32_16x16x32_bf16 v[10:13], v[2:5], v[10:13], 0
	s_waitcnt vmcnt(6)
	v_mfma_f32_16x16x32_bf16 v[2:5], v[2:5], v[14:17], 0
	global_load_dwordx4 v[14:17], v[88:89], off offset:128
	global_load_dwordx4 v[84:87], v[90:91], off offset:128
	s_waitcnt vmcnt(6)
	v_mfma_f32_16x16x32_bf16 v[6:9], v[18:21], v[22:25], v[6:9]
	global_load_dwordx4 v[22:25], v[30:31], off offset:192
	s_waitcnt vmcnt(6)
	v_mfma_f32_16x16x32_bf16 v[10:13], v[18:21], v[26:29], v[10:13]
	global_load_dwordx4 v[26:29], v[70:71], off offset:192
	s_waitcnt vmcnt(6)
	v_mfma_f32_16x16x32_bf16 v[2:5], v[18:21], v[60:63], v[2:5]
	global_load_dwordx4 v[18:21], v[88:89], off offset:192
	global_load_dwordx4 v[60:63], v[90:91], off offset:192
	s_waitcnt vmcnt(6)
	v_mfma_f32_16x16x32_bf16 v[6:9], v[64:67], v[80:83], v[6:9]
	s_waitcnt vmcnt(5)
	v_mfma_f32_16x16x32_bf16 v[10:13], v[64:67], v[14:17], v[10:13]
	global_load_dwordx4 v[14:17], v[30:31], off offset:256
	s_waitcnt vmcnt(5)
	v_mfma_f32_16x16x32_bf16 v[2:5], v[64:67], v[84:87], v[2:5]
	global_load_dwordx4 v[64:67], v[70:71], off offset:256
	s_waitcnt vmcnt(4)
	v_mfma_f32_16x16x32_bf16 v[6:9], v[22:25], v[26:29], v[6:9]
	global_load_dwordx4 v[26:29], v[88:89], off offset:256
	global_load_dwordx4 v[80:83], v[90:91], off offset:256
	s_waitcnt vmcnt(5)
	v_mfma_f32_16x16x32_bf16 v[10:13], v[22:25], v[18:21], v[10:13]
	global_load_dwordx4 v[18:21], v[30:31], off offset:320
	s_waitcnt vmcnt(5)
	v_mfma_f32_16x16x32_bf16 v[2:5], v[22:25], v[60:63], v[2:5]
	global_load_dwordx4 v[22:25], v[70:71], off offset:320
	s_waitcnt vmcnt(4)
	v_mfma_f32_16x16x32_bf16 v[6:9], v[14:17], v[64:67], v[6:9]
	global_load_dwordx4 v[60:63], v[88:89], off offset:320
	global_load_dwordx4 v[64:67], v[90:91], off offset:320
	s_waitcnt vmcnt(5)
	v_mfma_f32_16x16x32_bf16 v[10:13], v[14:17], v[26:29], v[10:13]
	global_load_dwordx4 v[26:29], v[30:31], off offset:384
	s_waitcnt vmcnt(5)
	v_mfma_f32_16x16x32_bf16 v[2:5], v[14:17], v[80:83], v[2:5]
	global_load_dwordx4 v[14:17], v[70:71], off offset:384
	s_waitcnt vmcnt(4)
	v_mfma_f32_16x16x32_bf16 v[6:9], v[18:21], v[22:25], v[6:9]
	global_load_dwordx4 v[22:25], v[88:89], off offset:384
	global_load_dwordx4 v[80:83], v[90:91], off offset:384
	s_waitcnt vmcnt(5)
	v_mfma_f32_16x16x32_bf16 v[10:13], v[18:21], v[60:63], v[10:13]
	global_load_dwordx4 v[60:63], v[30:31], off offset:448
	s_waitcnt vmcnt(5)
	v_mfma_f32_16x16x32_bf16 v[2:5], v[18:21], v[64:67], v[2:5]
	global_load_dwordx4 v[18:21], v[70:71], off offset:448
	s_waitcnt vmcnt(4)
	v_mfma_f32_16x16x32_bf16 v[6:9], v[26:29], v[14:17], v[6:9]
	global_load_dwordx4 v[14:17], v[88:89], off offset:448
	s_waitcnt vmcnt(4)
	v_mfma_f32_16x16x32_bf16 v[10:13], v[26:29], v[22:25], v[10:13]
	global_load_dwordx4 v[22:25], v[90:91], off offset:448
	s_add_i32 s47, s28, s70
	s_cmpk_gt_i32 s47, 0x23f
	s_cbranch_scc1 .Ln0_nopf
	v_readfirstlane_b32 s46, v69
	v_and_b32_e32 v94, 63, v166
	s_lshl_b32 s45, s47, 4
	v_lshlrev_b32_e32 v94, 4, v94
	s_add_u32 s45, s45, s46
	v_add_u32_e32 v95, 0x1000, v94
	s_sub_u32 s46, s45, 0x2000
	s_cmpk_ge_u32 s45, 0x2000
	s_cselect_b32 s98, s90, s92
	s_cselect_b32 s99, s91, s93
	s_cselect_b32 s46, s46, s45
	s_lshl_b32 s46, s46, 13
	s_add_u32 s98, s98, s46
	s_addc_u32 s99, s99, 0
	s_add_u32 s100, s98, 0x2000
	s_addc_u32 s101, s99, 0
	global_load_dwordx4 v[112:115], v94, s[98:99] offset:0 nt
	global_load_dwordx4 v[116:119], v94, s[98:99] offset:1024 nt
	global_load_dwordx4 v[120:123], v94, s[98:99] offset:2048 nt
	global_load_dwordx4 v[124:127], v94, s[98:99] offset:3072 nt
	global_load_dwordx4 v[128:131], v95, s[98:99] offset:0 nt
	global_load_dwordx4 v[132:135], v95, s[98:99] offset:1024 nt
	global_load_dwordx4 v[136:139], v95, s[98:99] offset:2048 nt
	global_load_dwordx4 v[140:143], v95, s[98:99] offset:3072 nt
	global_load_dwordx4 v[144:147], v94, s[100:101] offset:0 nt
	global_load_dwordx4 v[148:151], v94, s[100:101] offset:1024 nt
	global_load_dwordx4 v[152:155], v94, s[100:101] offset:2048 nt
	global_load_dwordx4 v[156:159], v94, s[100:101] offset:3072 nt
	global_load_dwordx4 v[160:163], v95, s[100:101] offset:0 nt
	global_load_dwordx4 v[232:235], v95, s[100:101] offset:1024 nt
	global_load_dwordx4 v[236:239], v95, s[100:101] offset:2048 nt
	global_load_dwordx4 v[240:243], v95, s[100:101] offset:3072 nt
	s_waitcnt vmcnt(20)
	v_mfma_f32_16x16x32_bf16 v[2:5], v[26:29], v[80:83], v[2:5]
	s_waitcnt vmcnt(18)
	v_mfma_f32_16x16x32_bf16 v[6:9], v[60:63], v[18:21], v[6:9]
	v_mul_u32_u24_e32 v18, 0xc0, v49
	v_lshlrev_b32_e32 v18, 2, v18
	s_waitcnt vmcnt(17)
	v_mfma_f32_16x16x32_bf16 v[10:13], v[60:63], v[14:17], v[10:13]
	v_add3_u32 v14, s29, v1, v18
	v_add3_u32 v1, s29, v18, v1
	s_waitcnt vmcnt(16)
	v_mfma_f32_16x16x32_bf16 v[2:5], v[60:63], v[22:25], v[2:5]
	s_branch .Ln0_join
; DI void skinny_tile(const P& p, int l, int r0, float* red) {
;     ...
; #pragma unroll
;     for (int n = 0; n < 3; ++n)
; #pragma unroll
;         for (int r = 0; r < 4; ++r) red[w * 768 + (4 * g + r) * 48 + 16 * n + l15] = acc[n][r];
;     __syncthreads();
;     for (int e = tid; e < 768; e += 512) {
;         float sum = 0.f;
; #pragma unroll
;         for (int k = 0; k < 8; ++k) sum += red[k * 768 + e];
;         G[(size_t)r0 * NNAR + e] = sum;
;     }
.Ln0_nopf:
	s_waitcnt vmcnt(4)
	v_mfma_f32_16x16x32_bf16 v[2:5], v[26:29], v[80:83], v[2:5]
	s_waitcnt vmcnt(2)
	v_mfma_f32_16x16x32_bf16 v[6:9], v[60:63], v[18:21], v[6:9]
	v_mul_u32_u24_e32 v18, 0xc0, v49
	v_lshlrev_b32_e32 v18, 2, v18
	s_waitcnt vmcnt(1)
	v_mfma_f32_16x16x32_bf16 v[10:13], v[60:63], v[14:17], v[10:13]
	v_add3_u32 v14, s29, v1, v18
	v_add3_u32 v1, s29, v18, v1
	s_waitcnt vmcnt(0)
	v_mfma_f32_16x16x32_bf16 v[2:5], v[60:63], v[22:25], v[2:5]
.Ln0_join:
	ds_write2_b32 v1, v7, v8 offset0:48 offset1:96
	ds_write_b32 v1, v9 offset:576
	s_nop 1
	ds_write2_b32 v14, v6, v10 offset1:16
	s_nop 2
	ds_write2_b32 v14, v2, v11 offset0:32 offset1:64
	ds_write2_b32 v14, v3, v12 offset0:80 offset1:112
	ds_write2_b32 v14, v4, v13 offset0:128 offset1:160
	ds_write_b32 v14, v5 offset:704
	s_waitcnt lgkmcnt(0)
	s_barrier
	s_and_saveexec_b64 s[18:19], vcc
	s_cbranch_execz .LBB0_96
	v_max_i32_e32 v1, 0x100, v0
	v_sub_u32_e32 v1, v1, v0
	v_add_u32_e32 v1, 0x1ff, v1
	v_cmp_lt_u32_e32 vcc, s42, v1
	s_mov_b64 s[22:23], -1
	s_and_saveexec_b64 s[20:21], vcc
	s_cbranch_execz .LBB0_112
	s_mul_hi_i32 s23, s24, 0xc0
	s_mulk_i32 s24, 0xc0
	v_lshrrev_b32_e32 v4, 9, v1
	s_add_u32 s22, s31, s24
	v_add_u32_e32 v1, 0x200, v0
	v_add_u32_e32 v5, -1, v4
	s_addc_u32 s23, s34, s23
	v_cmp_lt_u32_e32 vcc, 1, v5
	v_mov_b32_e32 v6, 0
	v_mov_b64_e32 v[2:3], v[0:1]
	s_and_saveexec_b64 s[24:25], vcc
	s_cbranch_execz .LBB0_109
	v_lshrrev_b32_e32 v2, 1, v5
	v_add_u32_e32 v2, 1, v2
	v_and_b32_e32 v6, -2, v2
	v_lshl_add_u32 v7, v0, 2, s29
	s_mov_b32 s44, 0
	s_mov_b64 s[26:27], 0
	v_mov_b64_e32 v[2:3], v[0:1]
